# P2: GLA sample state update with 16-byte loads and 8 loads in flight (swapped MFMA operands) + one GLA unit on the sample-attention workgroups
# speedup vs baseline: 1.0220x; 1.0054x over previous
; #define LAS __attribute__((address_space(3)))
; #define MFMA16(a, b, c) __builtin_amdgcn_mfma_f32_16x16x32_bf16((a), (b), (c), 0, 0, 0)
; template <int MODE, bool dry = false>
; __device__ __forceinline__ void gla_unit(const Args& a, LAS unsigned char* lds, int idx, int h, int tid, const float (&wu)[16], float bd) {
;     ...
;         for (int ks = 0; ks < KS_T; ++ks) { bf16x8 bv[2];
; #pragma unroll
;             for (int n = 0; n < 2; ++n) bv[n] = *(const LAS bf16x8*)(vT + (32 * wave + 16 * n + fr) * TT_P + 32 * ks + 8 * kq);
; #pragma unroll
;             for (int mt = 0; mt < 8; ++mt) { const bf16x8 av = *(const LAS bf16x8*)(klT + (16 * mt + fr) * TT_P + 32 * ks + 8 * kq);
; #pragma unroll
;                 for (int n = 0; n < 2; ++n) u[mt][n] = MFMA16(av, bv[n], u[mt][n]); } }
;     ...
;             const float* S0 = a.in[I_ST] + (size_t)(idx * 4 + h) * 32768; float* S1 = a.out + O_SS + (size_t)(idx * 4 + h) * 32768;
; #pragma unroll
;             for (int mt = 0; mt < 8; ++mt)
; #pragma unroll
;                 for (int n = 0; n < 2; ++n)
; #pragma unroll
;                     for (int i = 0; i < 4; ++i) { const int dk = 16 * mt + 4 * kq + i, dv = 32 * wave + 16 * n + fr; S1[dk * 256 + dv] = dvec[dk] * S0[dk * 256 + dv] + u[mt][n][i]; }
.LBB0_534:
	s_lshl_b32 s8, s10, 17
	s_lshl_b32 s9, s85, 15
	s_or_b32 s26, s8, s9
	s_lshl_b32 s87, s3, 5
	v_readlane_b32 s36, v252, 1
	v_or_b32_e32 v30, s87, v57
	s_lshl_b64 s[10:11], s[26:27], 2
	v_readlane_b32 s44, v252, 9
	v_readlane_b32 s45, v252, 10
	s_add_u32 s8, s44, s10
	s_addc_u32 s9, s45, s11
	v_mad_u64_u32 v[28:29], s[88:89], v30, s73, v[36:37]
	v_add_u32_e32 v31, v36, v63
	s_add_u32 s10, s74, s10
	s_addc_u32 s11, s75, s11
	v_mov_b32_e32 v47, v33
	v_lshrrev_b32_e32 v45, 4, v176
	v_mul_u32_u24_e32 v29, 0x3fc, v57
	v_lshl_add_u32 v29, v30, 2, v29
	v_lshl_add_u32 v29, v45, 4, v29
	v_lshlrev_b32_e32 v54, 2, v57
	v_add_u32_e32 v54, 0x18e00, v54
	s_mov_b64 s[88:89], s[8:9]
	ds_read_b128 v[20:23], v28 offset:53248
	ds_read_b128 v[16:19], v28 offset:55552
	ds_read_b128 v[128:131], v31 offset:34816
	ds_read_b128 v[132:135], v31 offset:37120
	ds_read_b32 v136, v54
	ds_read_b32 v137, v54 offset:64
	ds_read_b32 v138, v54 offset:128
	ds_read_b32 v139, v54 offset:192
	ds_read_b32 v140, v54 offset:256
	ds_read_b32 v141, v54 offset:320
	ds_read_b32 v142, v54 offset:384
	ds_read_b32 v143, v54 offset:448
	global_load_dwordx4 v[208:211], v29, s[88:89]
	global_load_dwordx4 v[212:215], v29, s[88:89] offset:64
	s_add_u32 s88, s88, 0x4000
	s_addc_u32 s89, s89, 0
	global_load_dwordx4 v[216:219], v29, s[88:89]
	global_load_dwordx4 v[220:223], v29, s[88:89] offset:64
	s_add_u32 s88, s88, 0x4000
	s_addc_u32 s89, s89, 0
	global_load_dwordx4 v[224:227], v29, s[88:89]
	global_load_dwordx4 v[228:231], v29, s[88:89] offset:64
	s_add_u32 s88, s88, 0x4000
	s_addc_u32 s89, s89, 0
	global_load_dwordx4 v[232:235], v29, s[88:89]
	global_load_dwordx4 v[236:239], v29, s[88:89] offset:64
	s_add_u32 s88, s88, 0x4000
	s_addc_u32 s89, s89, 0
	s_and_b32 s3, s86, 0x3fffffc0
	v_readlane_b32 s37, v252, 2
	v_readlane_b32 s38, v252, 3
	v_readlane_b32 s39, v252, 4
	v_readlane_b32 s40, v252, 5
	v_readlane_b32 s41, v252, 6
	v_readlane_b32 s42, v252, 7
	v_readlane_b32 s43, v252, 8
	v_readlane_b32 s46, v252, 11
	v_readlane_b32 s47, v252, 12
	v_readlane_b32 s48, v252, 13
	v_readlane_b32 s49, v252, 14
	v_readlane_b32 s50, v252, 15
	v_readlane_b32 s51, v252, 16
	s_waitcnt lgkmcnt(0)
	v_mfma_f32_16x16x32_bf16 v[120:123], v[20:23], v[128:131], 0
	v_mfma_f32_16x16x32_bf16 v[124:127], v[16:19], v[128:131], 0
	ds_read_b128 v[128:131], v31 offset:39424
	s_waitcnt vmcnt(6)
	s_nop 5
	v_fma_f32 v120, v136, v208, v120
	v_fma_f32 v121, v136, v209, v121
	v_fma_f32 v122, v136, v210, v122
	v_fma_f32 v123, v136, v211, v123
	v_fma_f32 v124, v136, v212, v124
	v_fma_f32 v125, v136, v213, v125
	v_fma_f32 v126, v136, v214, v126
	v_fma_f32 v127, v136, v215, v127
	global_store_dwordx4 v29, v[120:123], s[10:11]
	global_store_dwordx4 v29, v[124:127], s[10:11] offset:64
	s_add_u32 s10, s10, 0x4000
	s_addc_u32 s11, s11, 0
	global_load_dwordx4 v[208:211], v29, s[88:89]
	global_load_dwordx4 v[212:215], v29, s[88:89] offset:64
	s_add_u32 s88, s88, 0x4000
	s_addc_u32 s89, s89, 0
	s_waitcnt lgkmcnt(0)
	v_mfma_f32_16x16x32_bf16 v[120:123], v[20:23], v[132:135], 0
	v_mfma_f32_16x16x32_bf16 v[124:127], v[16:19], v[132:135], 0
	ds_read_b128 v[132:135], v31 offset:41728
	s_waitcnt vmcnt(8)
	s_nop 5
	v_fma_f32 v120, v137, v216, v120
	v_fma_f32 v121, v137, v217, v121
	v_fma_f32 v122, v137, v218, v122
	v_fma_f32 v123, v137, v219, v123
	v_fma_f32 v124, v137, v220, v124
	v_fma_f32 v125, v137, v221, v125
	v_fma_f32 v126, v137, v222, v126
	v_fma_f32 v127, v137, v223, v127
	global_store_dwordx4 v29, v[120:123], s[10:11]
	global_store_dwordx4 v29, v[124:127], s[10:11] offset:64
	s_add_u32 s10, s10, 0x4000
	s_addc_u32 s11, s11, 0
	global_load_dwordx4 v[216:219], v29, s[88:89]
	global_load_dwordx4 v[220:223], v29, s[88:89] offset:64
	s_add_u32 s88, s88, 0x4000
	s_addc_u32 s89, s89, 0
	s_waitcnt lgkmcnt(0)
	v_mfma_f32_16x16x32_bf16 v[120:123], v[20:23], v[128:131], 0
	v_mfma_f32_16x16x32_bf16 v[124:127], v[16:19], v[128:131], 0
	ds_read_b128 v[128:131], v31 offset:44032
	s_waitcnt vmcnt(10)
	s_nop 5
	v_fma_f32 v120, v138, v224, v120
	v_fma_f32 v121, v138, v225, v121
	v_fma_f32 v122, v138, v226, v122
	v_fma_f32 v123, v138, v227, v123
	v_fma_f32 v124, v138, v228, v124
	v_fma_f32 v125, v138, v229, v125
	v_fma_f32 v126, v138, v230, v126
	v_fma_f32 v127, v138, v231, v127
	global_store_dwordx4 v29, v[120:123], s[10:11]
	global_store_dwordx4 v29, v[124:127], s[10:11] offset:64
	s_add_u32 s10, s10, 0x4000
	s_addc_u32 s11, s11, 0
	global_load_dwordx4 v[224:227], v29, s[88:89]
	global_load_dwordx4 v[228:231], v29, s[88:89] offset:64
	s_add_u32 s88, s88, 0x4000
	s_addc_u32 s89, s89, 0
	s_waitcnt lgkmcnt(0)
	v_mfma_f32_16x16x32_bf16 v[120:123], v[20:23], v[132:135], 0
	v_mfma_f32_16x16x32_bf16 v[124:127], v[16:19], v[132:135], 0
	ds_read_b128 v[132:135], v31 offset:46336
	s_waitcnt vmcnt(12)
	s_nop 5
	v_fma_f32 v120, v139, v232, v120
	v_fma_f32 v121, v139, v233, v121
	v_fma_f32 v122, v139, v234, v122
	v_fma_f32 v123, v139, v235, v123
	v_fma_f32 v124, v139, v236, v124
	v_fma_f32 v125, v139, v237, v125
	v_fma_f32 v126, v139, v238, v126
	v_fma_f32 v127, v139, v239, v127
	global_store_dwordx4 v29, v[120:123], s[10:11]
	global_store_dwordx4 v29, v[124:127], s[10:11] offset:64
	s_add_u32 s10, s10, 0x4000
	s_addc_u32 s11, s11, 0
	global_load_dwordx4 v[232:235], v29, s[88:89]
	global_load_dwordx4 v[236:239], v29, s[88:89] offset:64
	s_add_u32 s88, s88, 0x4000
	s_addc_u32 s89, s89, 0
	s_waitcnt lgkmcnt(0)
	v_mfma_f32_16x16x32_bf16 v[120:123], v[20:23], v[128:131], 0
	v_mfma_f32_16x16x32_bf16 v[124:127], v[16:19], v[128:131], 0
	ds_read_b128 v[128:131], v31 offset:48640
	s_waitcnt vmcnt(12)
; #define LAS __attribute__((address_space(3)))
; __device__ __forceinline__ bf16x8 pk8(f32x4 a, f32x4 b) { u32x4 w; w.x = cvt_pk_bf16(a[0], a[1]); w.y = cvt_pk_bf16(a[2], a[3]); w.z = cvt_pk_bf16(b[0], b[1]); w.w = cvt_pk_bf16(b[2], b[3]); return __builtin_bit_cast(bf16x8, w); }
; #define MFMA16(a, b, c) __builtin_amdgcn_mfma_f32_16x16x32_bf16((a), (b), (c), 0, 0, 0)
; template <int MODE, bool dry = false>
; __device__ __forceinline__ void gla_unit(const Args& a, LAS unsigned char* lds, int idx, int h, int tid, const float (&wu)[16], float bd) {
;     ...
;             const float* S0 = a.in[I_ST] + (size_t)(idx * 4 + h) * 32768; float* S1 = a.out + O_SS + (size_t)(idx * 4 + h) * 32768;
; #pragma unroll
;             for (int mt = 0; mt < 8; ++mt)
; #pragma unroll
;                 for (int n = 0; n < 2; ++n)
; #pragma unroll
;                     for (int i = 0; i < 4; ++i) { const int dk = 16 * mt + 4 * kq + i, dv = 32 * wave + 16 * n + fr; S1[dk * 256 + dv] = dvec[dk] * S0[dk * 256 + dv] + u[mt][n][i]; }
;     ...
;         for (int ks = 0; ks < KS_T; ++ks) { bf16x8 av[2];
; #pragma unroll
;             for (int m = 0; m < 2; ++m) av[m] = *(const LAS bf16x8*)(vT + (32 * wave + 16 * m + fr) * TT_P + 32 * ks + 8 * kq);
; #pragma unroll
;             for (int nt = 0; nt < NTL; ++nt) { const bf16x8 bv = *(const LAS bf16x8*)(att + (16 * nt + fr) * TT_P + 32 * ks + 8 * kq);
; #pragma unroll
;                 for (int m = 0; m < 2; ++m) o[m][nt] = MFMA16(av[m], bv, o[m][nt]); } }
; #pragma unroll
;         for (int ks = 0; ks < 4; ++ks) { bf16x8 av[2];
; #pragma unroll
;             for (int m = 0; m < 2; ++m) { const int dv = 32 * wave + 16 * m + fr;
;                 if (MODE == 1) av[m] = sraw[ks][m];
;                 else { const float* sp = a.in[I_ST] + (size_t)(idx * 4 + h) * 32768 + (size_t)(32 * ks + 8 * kq) * 256 + dv; f32x4 x0, x1;
; #pragma unroll
;                     for (int j = 0; j < 4; ++j) { x0[j] = sp[j * 256]; x1[j] = sp[(j + 4) * 256]; }
;                     av[m] = pk8(x0, x1); } }
	s_nop 5
	v_fma_f32 v120, v140, v208, v120
	v_fma_f32 v121, v140, v209, v121
	v_fma_f32 v122, v140, v210, v122
	v_fma_f32 v123, v140, v211, v123
	v_fma_f32 v124, v140, v212, v124
	v_fma_f32 v125, v140, v213, v125
	v_fma_f32 v126, v140, v214, v126
	v_fma_f32 v127, v140, v215, v127
	global_store_dwordx4 v29, v[120:123], s[10:11]
	global_store_dwordx4 v29, v[124:127], s[10:11] offset:64
	s_add_u32 s10, s10, 0x4000
	s_addc_u32 s11, s11, 0
	s_waitcnt lgkmcnt(0)
	v_mfma_f32_16x16x32_bf16 v[120:123], v[20:23], v[132:135], 0
	v_mfma_f32_16x16x32_bf16 v[124:127], v[16:19], v[132:135], 0
	ds_read_b128 v[132:135], v31 offset:50944
	s_waitcnt vmcnt(10)
	s_nop 5
	v_fma_f32 v120, v141, v216, v120
	v_fma_f32 v121, v141, v217, v121
	v_fma_f32 v122, v141, v218, v122
	v_fma_f32 v123, v141, v219, v123
	v_fma_f32 v124, v141, v220, v124
	v_fma_f32 v125, v141, v221, v125
	v_fma_f32 v126, v141, v222, v126
	v_fma_f32 v127, v141, v223, v127
	global_store_dwordx4 v29, v[120:123], s[10:11]
	global_store_dwordx4 v29, v[124:127], s[10:11] offset:64
	s_add_u32 s10, s10, 0x4000
	s_addc_u32 s11, s11, 0
	s_waitcnt lgkmcnt(0)
	v_mfma_f32_16x16x32_bf16 v[120:123], v[20:23], v[128:131], 0
	v_mfma_f32_16x16x32_bf16 v[124:127], v[16:19], v[128:131], 0
	s_waitcnt vmcnt(8)
	s_nop 5
	v_fma_f32 v120, v142, v224, v120
	v_fma_f32 v121, v142, v225, v121
	v_fma_f32 v122, v142, v226, v122
	v_fma_f32 v123, v142, v227, v123
	v_fma_f32 v124, v142, v228, v124
	v_fma_f32 v125, v142, v229, v125
	v_fma_f32 v126, v142, v230, v126
	v_fma_f32 v127, v142, v231, v127
	global_store_dwordx4 v29, v[120:123], s[10:11]
	global_store_dwordx4 v29, v[124:127], s[10:11] offset:64
	s_add_u32 s10, s10, 0x4000
	s_addc_u32 s11, s11, 0
	s_waitcnt lgkmcnt(0)
	v_mfma_f32_16x16x32_bf16 v[120:123], v[20:23], v[132:135], 0
	v_mfma_f32_16x16x32_bf16 v[124:127], v[16:19], v[132:135], 0
	s_waitcnt vmcnt(6)
	s_nop 5
	v_fma_f32 v120, v143, v232, v120
	v_fma_f32 v121, v143, v233, v121
	v_fma_f32 v122, v143, v234, v122
	v_fma_f32 v123, v143, v235, v123
	v_fma_f32 v124, v143, v236, v124
	v_fma_f32 v125, v143, v237, v125
	v_fma_f32 v126, v143, v238, v126
	v_fma_f32 v127, v143, v239, v127
	global_store_dwordx4 v29, v[120:123], s[10:11]
	global_store_dwordx4 v29, v[124:127], s[10:11] offset:64
	s_add_u32 s10, s10, 0x4000
	s_addc_u32 s11, s11, 0
	v_mov_b32_e32 v31, v33
	v_lshl_add_u64 v[22:23], s[8:9], 0, v[46:47]
	v_lshl_add_u64 v[54:55], v[22:23], 0, s[66:67]
	v_mov_b32_e32 v17, v33
	v_lshlrev_b64 v[20:21], 2, v[30:31]
	v_lshl_add_u64 v[24:25], v[22:23], 0, v[20:21]
	v_add_co_u32_e32 v116, vcc, s72, v24
	v_or_b32_e32 v16, 16, v30
	s_nop 0
	v_addc_co_u32_e32 v117, vcc, 0, v25, vcc
	v_lshl_add_u64 v[30:31], v[22:23], 0, s[64:65]
	v_lshl_add_u64 v[118:119], v[30:31], 0, v[20:21]
	v_lshlrev_b64 v[16:17], 2, v[16:17]
	v_add_co_u32_e32 v128, vcc, s72, v118
	v_lshl_add_u64 v[30:31], v[30:31], 0, v[16:17]
	s_nop 0
	v_addc_co_u32_e32 v129, vcc, 0, v119, vcc
	v_lshl_add_u64 v[22:23], v[22:23], 0, s[68:69]
	v_add_co_u32_e32 v130, vcc, s72, v30
	v_lshl_add_u64 v[120:121], v[54:55], 0, v[20:21]
	v_lshl_add_u64 v[54:55], v[54:55], 0, v[16:17]
	v_lshl_add_u64 v[124:125], v[22:23], 0, v[20:21]
	v_lshl_add_u64 v[126:127], v[22:23], 0, v[16:17]
	v_addc_co_u32_e32 v131, vcc, 0, v31, vcc
	v_add_co_u32_e32 v132, vcc, s72, v120
	s_barrier
	global_load_dword v32, v[24:25], off
	global_load_dword v45, v[24:25], off offset:1024
	global_load_dword v47, v[24:25], off offset:2048
	global_load_dword v49, v[24:25], off offset:3072
	global_load_dword v53, v[24:25], off offset:3136
	global_load_dword v115, v[24:25], off offset:2112
	global_load_dword v138, v[24:25], off offset:1088
	global_load_dword v139, v[24:25], off offset:64
	global_load_dword v140, v[116:117], off
	global_load_dword v141, v[116:117], off offset:1024
	global_load_dword v142, v[116:117], off offset:2048
	global_load_dword v143, v[116:117], off offset:3072
	global_load_dword v144, v[116:117], off offset:3136
	global_load_dword v145, v[116:117], off offset:2112
	global_load_dword v146, v[116:117], off offset:1088
	global_load_dword v147, v[116:117], off offset:64
	ds_read_b128 v[16:19], v28 offset:53248
	ds_read_b128 v[20:23], v28 offset:55552
	global_load_dword v148, v[118:119], off
	global_load_dword v149, v[128:129], off
	global_load_dword v150, v[118:119], off offset:1024
	global_load_dword v151, v[128:129], off offset:1024
	global_load_dword v152, v[118:119], off offset:2048
	global_load_dword v153, v[128:129], off offset:2048
	global_load_dword v154, v[128:129], off offset:3072
	global_load_dword v155, v[118:119], off offset:3072
	global_load_dword v156, v[30:31], off
	global_load_dword v157, v[130:131], off
	global_load_dword v158, v[30:31], off offset:1024
	global_load_dword v159, v[130:131], off offset:1024
	global_load_dword v160, v[30:31], off offset:2048
	global_load_dword v161, v[130:131], off offset:2048
	global_load_dword v162, v[130:131], off offset:3072
	global_load_dword v163, v[30:31], off offset:3072
	v_addc_co_u32_e32 v133, vcc, 0, v121, vcc
	v_add_co_u32_e32 v134, vcc, s72, v54
	ds_read_b128 v[24:27], v109
	ds_read_b128 v[28:31], v109 offset:2304
	v_addc_co_u32_e32 v135, vcc, 0, v55, vcc
	global_load_dword v164, v[120:121], off
	global_load_dword v165, v[132:133], off
	global_load_dword v166, v[120:121], off offset:1024
	global_load_dword v167, v[132:133], off offset:1024
	global_load_dword v168, v[120:121], off offset:2048
	global_load_dword v169, v[132:133], off offset:2048
	global_load_dword v170, v[132:133], off offset:3072
	global_load_dword v171, v[120:121], off offset:3072
	global_load_dword v172, v[54:55], off
	global_load_dword v173, v[134:135], off
	global_load_dword v174, v[54:55], off offset:1024
	global_load_dword v175, v[134:135], off offset:1024
	global_load_dword v177, v[54:55], off offset:2048
	global_load_dword v179, v[134:135], off offset:2048
	global_load_dword v180, v[134:135], off offset:3072
	s_nop 0
	global_load_dword v54, v[54:55], off offset:3072
	v_add_co_u32_e32 v136, vcc, s72, v124
	s_waitcnt lgkmcnt(1)
; #define LAS __attribute__((address_space(3)))
; __device__ __forceinline__ bf16x8 pk8(f32x4 a, f32x4 b) { u32x4 w; w.x = cvt_pk_bf16(a[0], a[1]); w.y = cvt_pk_bf16(a[2], a[3]); w.z = cvt_pk_bf16(b[0], b[1]); w.w = cvt_pk_bf16(b[2], b[3]); return __builtin_bit_cast(bf16x8, w); }
; #define MFMA16(a, b, c) __builtin_amdgcn_mfma_f32_16x16x32_bf16((a), (b), (c), 0, 0, 0)
; template <int MODE, bool dry = false>
; __device__ __forceinline__ void gla_unit(const Args& a, LAS unsigned char* lds, int idx, int h, int tid, const float (&wu)[16], float bd) {
;     ...
;         for (int ks = 0; ks < KS_T; ++ks) { bf16x8 av[2];
; #pragma unroll
;             for (int m = 0; m < 2; ++m) av[m] = *(const LAS bf16x8*)(vT + (32 * wave + 16 * m + fr) * TT_P + 32 * ks + 8 * kq);
; #pragma unroll
;             for (int nt = 0; nt < NTL; ++nt) { const bf16x8 bv = *(const LAS bf16x8*)(att + (16 * nt + fr) * TT_P + 32 * ks + 8 * kq);
; #pragma unroll
;                 for (int m = 0; m < 2; ++m) o[m][nt] = MFMA16(av[m], bv, o[m][nt]); } }
; #pragma unroll
;         for (int ks = 0; ks < 4; ++ks) { bf16x8 av[2];
; #pragma unroll
;             for (int m = 0; m < 2; ++m) { const int dv = 32 * wave + 16 * m + fr;
;                 if (MODE == 1) av[m] = sraw[ks][m];
;                 else { const float* sp = a.in[I_ST] + (size_t)(idx * 4 + h) * 32768 + (size_t)(32 * ks + 8 * kq) * 256 + dv; f32x4 x0, x1;
; #pragma unroll
;                     for (int j = 0; j < 4; ++j) { x0[j] = sp[j * 256]; x1[j] = sp[(j + 4) * 256]; }
;                     av[m] = pk8(x0, x1); } }
; #pragma unroll
;             for (int nt = 0; nt < NTL; ++nt) { const bf16x8 bv = *(const LAS bf16x8*)(qe + (16 * nt + fr) * QE_P + 32 * ks + 8 * kq);
; #pragma unroll
;                 for (int m = 0; m < 2; ++m) o[m][nt] = MFMA16(av[m], bv, o[m][nt]); } }
; #pragma unroll
;         for (int nt = 0; nt < NTL; ++nt) { float ss = 0.f;
; #pragma unroll
;             for (int m = 0; m < 2; ++m) ss += (o[m][nt][0] * o[m][nt][0] + o[m][nt][1] * o[m][nt][1]) + (o[m][nt][2] * o[m][nt][2] + o[m][nt][3] * o[m][nt][3]);
;             ss += __shfl_xor(ss, 16); ss += __shfl_xor(ss, 32);
;             if (kq == 0) red[wave * 64 + 16 * nt + fr] = ss; }
	v_mfma_f32_16x16x32_bf16 v[116:119], v[16:19], v[24:27], 0
	v_addc_co_u32_e32 v137, vcc, 0, v125, vcc
	v_add_co_u32_e32 v122, vcc, s72, v126
	global_load_dword v55, v[124:125], off
	global_load_dword v181, v[136:137], off
	global_load_dword v182, v[124:125], off offset:1024
	global_load_dword v183, v[136:137], off offset:1024
	global_load_dword v184, v[124:125], off offset:2048
	global_load_dword v185, v[136:137], off offset:2048
	global_load_dword v186, v[136:137], off offset:3072
	global_load_dword v187, v[124:125], off offset:3072
	v_addc_co_u32_e32 v123, vcc, 0, v127, vcc
	global_load_dword v188, v[126:127], off
	global_load_dword v189, v[126:127], off offset:1024
	global_load_dword v190, v[122:123], off offset:1024
	global_load_dword v191, v[126:127], off offset:2048
	global_load_dword v192, v[122:123], off offset:2048
	global_load_dword v193, v[122:123], off offset:3072
	global_load_dword v194, v[126:127], off offset:3072
	global_load_dword v195, v[122:123], off
	v_mfma_f32_16x16x32_bf16 v[24:27], v[20:23], v[24:27], 0
	ds_read_b128 v[120:123], v110
	ds_read_b128 v[124:127], v110 offset:64
	s_waitcnt vmcnt(62)
	v_cvt_pk_bf16_f32 v128, v32, v45
	s_waitcnt lgkmcnt(2)
	v_mfma_f32_16x16x32_bf16 v[16:19], v[16:19], v[28:31], 0
	s_waitcnt vmcnt(60)
	v_cvt_pk_bf16_f32 v129, v47, v49
	s_waitcnt vmcnt(45)
	v_cvt_pk_bf16_f32 v136, v148, v150
	v_cvt_pk_bf16_f32 v130, v140, v141
	v_mfma_f32_16x16x32_bf16 v[20:23], v[20:23], v[28:31], 0
	v_cvt_pk_bf16_f32 v131, v142, v143
	v_cvt_pk_bf16_f32 v28, v139, v138
	v_cvt_pk_bf16_f32 v29, v115, v53
	v_cvt_pk_bf16_f32 v31, v145, v144
	v_cvt_pk_bf16_f32 v30, v147, v146
	s_waitcnt lgkmcnt(1)
	v_mfma_f32_16x16x32_bf16 v[116:119], v[128:131], v[120:123], v[116:119]
	s_waitcnt vmcnt(40)
	v_cvt_pk_bf16_f32 v137, v152, v155
	v_cvt_pk_bf16_f32 v138, v149, v151
	v_cvt_pk_bf16_f32 v139, v153, v154
	v_mfma_f32_16x16x32_bf16 v[24:27], v[28:31], v[120:123], v[24:27]
	ds_read_b128 v[120:123], v110 offset:4352
	ds_read_b128 v[132:135], v110 offset:4416
	s_waitcnt lgkmcnt(1)
	v_mfma_f32_16x16x32_bf16 v[20:23], v[28:31], v[120:123], v[20:23]
	s_waitcnt vmcnt(37)
	v_cvt_pk_bf16_f32 v28, v156, v158
	s_waitcnt vmcnt(32)
	v_cvt_pk_bf16_f32 v29, v160, v163
	v_cvt_pk_bf16_f32 v30, v157, v159
	v_cvt_pk_bf16_f32 v31, v161, v162
	v_mfma_f32_16x16x32_bf16 v[16:19], v[128:131], v[120:123], v[16:19]
	s_waitcnt vmcnt(29)
	v_cvt_pk_bf16_f32 v128, v164, v166
	s_waitcnt vmcnt(24)
	v_cvt_pk_bf16_f32 v129, v168, v171
	v_cvt_pk_bf16_f32 v130, v165, v167
	v_mfma_f32_16x16x32_bf16 v[116:119], v[136:139], v[124:127], v[116:119]
	v_cvt_pk_bf16_f32 v131, v169, v170
	v_mfma_f32_16x16x32_bf16 v[24:27], v[28:31], v[124:127], v[24:27]
	ds_read_b128 v[120:123], v110 offset:128
	ds_read_b128 v[124:127], v110 offset:192
	s_waitcnt lgkmcnt(2)
	v_mfma_f32_16x16x32_bf16 v[16:19], v[136:139], v[132:135], v[16:19]
	s_waitcnt vmcnt(13)
	v_cvt_pk_bf16_f32 v136, v55, v182
	s_waitcnt vmcnt(8)
	v_cvt_pk_bf16_f32 v137, v184, v187
	v_cvt_pk_bf16_f32 v138, v181, v183
	v_mfma_f32_16x16x32_bf16 v[20:23], v[28:31], v[132:135], v[20:23]
	v_cvt_pk_bf16_f32 v28, v172, v174
	v_cvt_pk_bf16_f32 v29, v177, v54
	v_cvt_pk_bf16_f32 v30, v173, v175
	v_cvt_pk_bf16_f32 v31, v179, v180
	ds_read_b128 v[132:135], v110 offset:4480
	s_waitcnt lgkmcnt(2)
	v_mfma_f32_16x16x32_bf16 v[116:119], v[128:131], v[120:123], v[116:119]
	v_cvt_pk_bf16_f32 v139, v185, v186
	v_mfma_f32_16x16x32_bf16 v[24:27], v[28:31], v[120:123], v[24:27]
	ds_read_b128 v[120:123], v110 offset:4544
	s_waitcnt lgkmcnt(1)
	v_mfma_f32_16x16x32_bf16 v[16:19], v[128:131], v[132:135], v[16:19]
	s_waitcnt vmcnt(6)
	v_cvt_pk_bf16_f32 v128, v188, v189
	s_waitcnt vmcnt(1)
	v_cvt_pk_bf16_f32 v129, v191, v194
	s_waitcnt vmcnt(0)
	v_cvt_pk_bf16_f32 v130, v195, v190
	v_cvt_pk_bf16_f32 v131, v192, v193
	v_mfma_f32_16x16x32_bf16 v[132:135], v[28:31], v[132:135], v[20:23]
	v_mfma_f32_16x16x32_bf16 v[28:31], v[136:139], v[124:127], v[116:119]
	s_nop 1
	v_and_b32_e32 v21, 64, v114
	v_xor_b32_e32 v20, 16, v114
	v_add_u32_e32 v45, 64, v21
	v_mfma_f32_16x16x32_bf16 v[24:27], v[128:131], v[124:127], v[24:27]
	v_cmp_lt_i32_e32 vcc, v20, v45
	s_nop 1
	v_cndmask_b32_e32 v20, v114, v20, vcc
	v_lshlrev_b32_e32 v32, 2, v20
	s_waitcnt lgkmcnt(0)
	v_mfma_f32_16x16x32_bf16 v[20:23], v[136:139], v[120:123], v[16:19]
	s_nop 2
	v_mul_f32_e32 v16, v29, v29
	v_mul_f32_e32 v17, v31, v31
	v_mul_f32_e32 v18, v25, v25
	v_mul_f32_e32 v19, v27, v27
	v_fmac_f32_e32 v16, v28, v28
	v_fmac_f32_e32 v17, v30, v30
	v_fmac_f32_e32 v18, v24, v24
	v_fmac_f32_e32 v19, v26, v26
	v_add_f32_e32 v16, v16, v17
	v_add_f32_e32 v17, v18, v19
	v_add_f32_e32 v16, v16, v17
	ds_bpermute_b32 v17, v32, v16
	v_xor_b32_e32 v18, 32, v114
	v_cmp_lt_i32_e32 vcc, v18, v45
	v_lshl_add_u32 v45, s3, 2, v65
	s_waitcnt lgkmcnt(0)
	v_add_f32_e32 v49, v16, v17
	v_cndmask_b32_e32 v18, v114, v18, vcc
	v_lshlrev_b32_e32 v47, 2, v18
	ds_bpermute_b32 v53, v47, v49
	v_mfma_f32_16x16x32_bf16 v[16:19], v[128:131], v[120:123], v[132:135]
	s_and_saveexec_b64 s[8:9], s[6:7]
	s_cbranch_execz .LBB0_536
	s_waitcnt lgkmcnt(0)
	v_add_f32_e32 v49, v49, v53
	ds_write_b32 v45, v49
